# P8 K-loop: first iteration of every tile after the first peeled, its first two waits let the previous tile's 8 G stores stay outstanding (vmcnt 16)
# baseline (speedup 1.0000x reference)
.LBB0_731:
	s_add_u32 s4, s76, 0x3ca00000
	s_addc_u32 s5, s77, 0
	s_cmp_lt_i32 s78, 13
	s_cselect_b64 s[2:3], -1, 0
	s_cmp_gt_i32 s79, 12
	s_cselect_b64 s[6:7], -1, 0
	s_and_b64 s[2:3], s[2:3], s[6:7]
	s_andn2_b64 vcc, exec, s[2:3]
	s_cbranch_vccnz .LBB0_855
	s_mov_b32 s100, 0
	s_mov_b32 s98, -1
	v_mov_b32_e32 v0, v214
	s_mov_b32 s18, s73
	s_mov_b32 s19, s69
	s_waitcnt vmcnt(0)
	v_mov_b32_e32 v14, v214
	s_cmpk_lt_i32 s19, 0x1600
	s_cselect_b64 s[2:3], -1, 0
	s_cmpk_gt_i32 s19, 0x15ff
	v_readfirstlane_b32 s14, v14
	s_cbranch_scc1 .LBB0_735
	s_ashr_i32 s6, s19, 31
	s_lshr_b32 s6, s6, 29
	s_add_i32 s6, s19, s6
	s_ashr_i32 s7, s6, 3
	s_and_b32 s6, s6, -8
	s_sub_i32 s6, s19, s6
	s_cmp_lt_i32 s6, 0
	s_movk_i32 s8, 0x2c1
	s_cselect_b32 s8, s8, 0x2c0
	s_mul_i32 s6, s6, s8
	s_add_i32 s6, s6, s7
	s_mul_hi_i32 s7, s6, 0x2e8ba2e9
	s_lshr_b32 s8, s7, 31
	s_ashr_i32 s7, s7, 5
	s_add_i32 s7, s7, s8
	s_lshl_b32 s8, s7, 3
	s_mulk_i32 s7, 0xb0
	s_sub_i32 s6, s6, s7
	s_bfe_u32 s7, s6, 0x3001c
	s_add_i32 s7, s6, s7
	s_sext_i32_i16 s9, s7
	s_and_b32 s7, s7, 0xfff8
	s_sub_i32 s6, s6, s7
	s_sext_i32_i16 s6, s6
	s_add_i32 s10, s8, s6
	s_ashr_i32 s12, s9, 3
	s_andn2_b64 vcc, exec, s[2:3]
	s_cbranch_vccz .LBB0_736

.LBB0_743:
	s_ashr_i32 s81, s80, 31
	s_lshl_b64 s[14:15], s[80:81], 19
	s_add_u32 s82, s96, s14
	s_addc_u32 s83, s97, s15
	s_and_b64 s[14:15], s[44:45], exec
	s_cselect_b32 s11, s83, s47
	s_cselect_b32 s14, s82, s46
	s_ashr_i32 s75, s74, 31
	s_lshl_b64 s[16:17], s[74:75], 19
	v_readlane_b32 s24, v254, 6
	v_readlane_b32 s25, v254, 7
	s_add_u32 s84, s24, s16
	s_addc_u32 s85, s25, s17
	s_and_b64 s[16:17], s[44:45], exec
	s_cselect_b32 s15, s85, s49
	s_cselect_b32 s16, s84, s48
	s_add_u32 s46, s46, 0x40080
	s_addc_u32 s47, s47, 0
	s_add_u32 s17, s48, 0x100
	v_mov_b32_e32 v64, 0
	s_addc_u32 s24, s49, 0
	s_mov_b32 s25, -2
	v_mov_b64_e32 v[0:1], 0
	v_mov_b64_e32 v[2:3], 0
	v_mov_b64_e32 v[4:5], 0
	v_mov_b64_e32 v[6:7], 0
	v_mov_b64_e32 v[8:9], 0
	v_mov_b64_e32 v[10:11], 0
	v_mov_b64_e32 v[12:13], 0
	v_mov_b64_e32 v[14:15], 0
	v_mov_b64_e32 v[16:17], 0
	v_mov_b64_e32 v[18:19], 0
	v_mov_b64_e32 v[20:21], 0
	v_mov_b64_e32 v[22:23], 0
	v_mov_b64_e32 v[24:25], 0
	v_mov_b64_e32 v[26:27], 0
	v_mov_b64_e32 v[28:29], 0
	v_mov_b64_e32 v[30:31], 0
	v_mov_b64_e32 v[32:33], 0
	v_mov_b64_e32 v[34:35], 0
	v_mov_b64_e32 v[36:37], 0
	v_mov_b64_e32 v[38:39], 0
	v_mov_b64_e32 v[40:41], 0
	v_mov_b64_e32 v[42:43], 0
	v_mov_b64_e32 v[44:45], 0
	v_mov_b64_e32 v[46:47], 0
	v_mov_b64_e32 v[48:49], 0
	v_mov_b64_e32 v[50:51], 0
	v_mov_b64_e32 v[52:53], 0
	v_mov_b64_e32 v[54:55], 0
	v_mov_b64_e32 v[56:57], 0
	v_mov_b64_e32 v[58:59], 0
	v_mov_b64_e32 v[60:61], 0
	v_mov_b64_e32 v[62:63], 0
	v_mov_b64_e32 v[64:65], 0
	v_mov_b64_e32 v[66:67], 0
	v_mov_b64_e32 v[68:69], 0
	v_mov_b64_e32 v[70:71], 0
	v_mov_b64_e32 v[72:73], 0
	v_mov_b64_e32 v[74:75], 0
	v_mov_b64_e32 v[76:77], 0
	v_mov_b64_e32 v[78:79], 0
	v_mov_b64_e32 v[96:97], 0
	v_mov_b64_e32 v[98:99], 0
	v_mov_b64_e32 v[100:101], 0
	v_mov_b64_e32 v[102:103], 0
	v_mov_b64_e32 v[104:105], 0
	v_mov_b64_e32 v[106:107], 0
	v_mov_b64_e32 v[108:109], 0
	v_mov_b64_e32 v[110:111], 0
	v_mov_b64_e32 v[112:113], 0
	v_mov_b64_e32 v[114:115], 0
	v_mov_b64_e32 v[116:117], 0
	v_mov_b64_e32 v[118:119], 0
	v_mov_b64_e32 v[120:121], 0
	v_mov_b64_e32 v[122:123], 0
	v_mov_b64_e32 v[124:125], 0
	v_mov_b64_e32 v[126:127], 0
	v_mov_b64_e32 v[136:137], 0
	v_mov_b64_e32 v[138:139], 0
	v_mov_b64_e32 v[140:141], 0
	v_mov_b64_e32 v[142:143], 0
	v_mov_b64_e32 v[144:145], 0
	v_mov_b64_e32 v[146:147], 0
	v_mov_b64_e32 v[148:149], 0
	v_mov_b64_e32 v[150:151], 0
	s_cmp_eq_u32 s100, 0
	s_mov_b32 s100, 1
	s_cbranch_scc1 .Lp8_nopeel
	s_cmp_eq_u32 s99, 0
	s_cbranch_scc0 .Lprio_LBB0_744p
	s_setprio 1
.Lprio_LBB0_744p:
	ds_read_b128 v[80:83], v226
	ds_read_b128 v[84:87], v226 offset:1024
	ds_read_b128 v[88:91], v226 offset:2048
	ds_read_b128 v[92:95], v226 offset:3072
	ds_read_b128 v[128:131], v227
	ds_read_b128 v[132:135], v227 offset:1024
	ds_read_b128 v[152:155], v227 offset:2048
	ds_read_b128 v[156:159], v227 offset:3072
	s_add_u32 s26, s46, 0xfffc0080
	s_addc_u32 s27, s47, -1
	s_cmp_eq_u32 s25, 12
	s_cselect_b32 s89, s11, s27
	s_cselect_b32 s88, s14, s26
	s_cselect_b32 s49, s15, s24
	s_cselect_b32 s48, s16, s17
	s_add_i32 m0, s13, 0xc000
	ds_read_b128 v[160:163], v228
	ds_read_b128 v[164:167], v228 offset:1024
	ds_read_b128 v[168:171], v228 offset:2048
	ds_read_b128 v[172:175], v228 offset:3072
	ds_read_b128 v[192:195], v228 offset:4096
	ds_read_b128 v[196:199], v228 offset:5120
	ds_read_b128 v[200:203], v228 offset:6144
	ds_read_b128 v[204:207], v228 offset:7168
	global_load_lds_dwordx4 v184, s[46:47]
	s_add_i32 m0, s13, 0xe000
	s_nop 0
	global_load_lds_dwordx4 v186, s[46:47]
	s_waitcnt vmcnt(16)
	s_waitcnt lgkmcnt(0)
	s_barrier
	s_waitcnt lgkmcnt(0)
	v_mfma_f32_16x16x32_bf16 v[76:79], v[80:83], v[160:163], v[76:79]
	v_mfma_f32_16x16x32_bf16 v[64:67], v[88:91], v[160:163], v[64:67]
	v_mfma_f32_16x16x32_bf16 v[148:151], v[80:83], v[168:171], v[148:151]
	v_mfma_f32_16x16x32_bf16 v[140:143], v[88:91], v[168:171], v[140:143]
	v_mfma_f32_16x16x32_bf16 v[124:127], v[80:83], v[192:195], v[124:127]
	v_mfma_f32_16x16x32_bf16 v[120:123], v[88:91], v[192:195], v[120:123]
	v_mfma_f32_16x16x32_bf16 v[72:75], v[80:83], v[200:203], v[72:75]
	v_mfma_f32_16x16x32_bf16 v[60:63], v[88:91], v[200:203], v[60:63]
	v_mfma_f32_16x16x32_bf16 v[76:79], v[84:87], v[164:167], v[76:79]
	v_mfma_f32_16x16x32_bf16 v[64:67], v[92:95], v[164:167], v[64:67]
	v_mfma_f32_16x16x32_bf16 v[148:151], v[84:87], v[172:175], v[148:151]
	v_mfma_f32_16x16x32_bf16 v[140:143], v[92:95], v[172:175], v[140:143]
	v_mfma_f32_16x16x32_bf16 v[124:127], v[84:87], v[196:199], v[124:127]
	v_mfma_f32_16x16x32_bf16 v[120:123], v[92:95], v[196:199], v[120:123]
	v_mfma_f32_16x16x32_bf16 v[72:75], v[84:87], v[204:207], v[72:75]
	v_mfma_f32_16x16x32_bf16 v[60:63], v[92:95], v[204:207], v[60:63]
	v_mfma_f32_16x16x32_bf16 v[144:147], v[128:131], v[160:163], v[144:147]
	v_mfma_f32_16x16x32_bf16 v[136:139], v[152:155], v[160:163], v[136:139]
	v_mfma_f32_16x16x32_bf16 v[116:119], v[128:131], v[168:171], v[116:119]
	v_mfma_f32_16x16x32_bf16 v[112:115], v[152:155], v[168:171], v[112:115]
	v_mfma_f32_16x16x32_bf16 v[108:111], v[128:131], v[192:195], v[108:111]
	v_mfma_f32_16x16x32_bf16 v[104:107], v[152:155], v[192:195], v[104:107]
	v_mfma_f32_16x16x32_bf16 v[100:103], v[128:131], v[200:203], v[100:103]
	v_mfma_f32_16x16x32_bf16 v[96:99], v[152:155], v[200:203], v[96:99]
	v_mfma_f32_16x16x32_bf16 v[144:147], v[132:135], v[164:167], v[144:147]
	v_mfma_f32_16x16x32_bf16 v[136:139], v[156:159], v[164:167], v[136:139]
	v_mfma_f32_16x16x32_bf16 v[116:119], v[132:135], v[172:175], v[116:119]
	v_mfma_f32_16x16x32_bf16 v[112:115], v[156:159], v[172:175], v[112:115]
	v_mfma_f32_16x16x32_bf16 v[108:111], v[132:135], v[196:199], v[108:111]
	v_mfma_f32_16x16x32_bf16 v[104:107], v[156:159], v[196:199], v[104:107]
	v_mfma_f32_16x16x32_bf16 v[100:103], v[132:135], v[204:207], v[100:103]
	v_mfma_f32_16x16x32_bf16 v[96:99], v[156:159], v[204:207], v[96:99]
	s_barrier
	s_add_i32 s26, s3, s20
	s_mov_b32 m0, s26
	ds_read_b128 v[160:163], v228 offset:16384
	ds_read_b128 v[164:167], v228 offset:17408
	ds_read_b128 v[168:171], v228 offset:18432
	ds_read_b128 v[172:175], v228 offset:19456
	ds_read_b128 v[192:195], v228 offset:20480
	ds_read_b128 v[196:199], v228 offset:21504
	ds_read_b128 v[200:203], v228 offset:22528
	ds_read_b128 v[204:207], v228 offset:23552
	global_load_lds_dwordx4 v178, s[48:49]
	s_add_i32 m0, s26, 0x2000
	s_add_u32 s26, s48, 0x40000
	s_addc_u32 s27, s49, 0
	s_add_i32 s28, s93, s20
	global_load_lds_dwordx4 v182, s[48:49]
	s_mov_b32 m0, s28
	s_nop 0
	global_load_lds_dwordx4 v178, s[26:27]
	s_add_i32 m0, s28, 0x2000
	s_nop 0
	global_load_lds_dwordx4 v182, s[26:27]
	s_mov_b32 m0, s13
	s_nop 0
	global_load_lds_dwordx4 v176, s[88:89]
	s_mov_b32 m0, s21
	s_nop 0
	global_load_lds_dwordx4 v180, s[88:89]
	s_waitcnt vmcnt(16)
	s_waitcnt lgkmcnt(0)
	s_barrier
	s_waitcnt lgkmcnt(0)
	v_mfma_f32_16x16x32_bf16 v[68:71], v[80:83], v[160:163], v[68:71]
	v_mfma_f32_16x16x32_bf16 v[36:39], v[88:91], v[160:163], v[36:39]
	v_mfma_f32_16x16x32_bf16 v[52:55], v[80:83], v[168:171], v[52:55]
	v_mfma_f32_16x16x32_bf16 v[44:47], v[88:91], v[168:171], v[44:47]
	v_mfma_f32_16x16x32_bf16 v[28:31], v[80:83], v[192:195], v[28:31]
	v_mfma_f32_16x16x32_bf16 v[24:27], v[88:91], v[192:195], v[24:27]
	v_mfma_f32_16x16x32_bf16 v[56:59], v[80:83], v[200:203], v[56:59]
	v_mfma_f32_16x16x32_bf16 v[32:35], v[88:91], v[200:203], v[32:35]
	v_mfma_f32_16x16x32_bf16 v[68:71], v[84:87], v[164:167], v[68:71]
	v_mfma_f32_16x16x32_bf16 v[36:39], v[92:95], v[164:167], v[36:39]
	v_mfma_f32_16x16x32_bf16 v[52:55], v[84:87], v[172:175], v[52:55]
	v_mfma_f32_16x16x32_bf16 v[44:47], v[92:95], v[172:175], v[44:47]
	v_mfma_f32_16x16x32_bf16 v[28:31], v[84:87], v[196:199], v[28:31]
	v_mfma_f32_16x16x32_bf16 v[24:27], v[92:95], v[196:199], v[24:27]
	v_mfma_f32_16x16x32_bf16 v[56:59], v[84:87], v[204:207], v[56:59]
	v_mfma_f32_16x16x32_bf16 v[32:35], v[92:95], v[204:207], v[32:35]
	v_mfma_f32_16x16x32_bf16 v[48:51], v[128:131], v[160:163], v[48:51]
	v_mfma_f32_16x16x32_bf16 v[40:43], v[152:155], v[160:163], v[40:43]
	v_mfma_f32_16x16x32_bf16 v[20:23], v[128:131], v[168:171], v[20:23]
	v_mfma_f32_16x16x32_bf16 v[16:19], v[152:155], v[168:171], v[16:19]
	v_mfma_f32_16x16x32_bf16 v[12:15], v[128:131], v[192:195], v[12:15]
	v_mfma_f32_16x16x32_bf16 v[8:11], v[152:155], v[192:195], v[8:11]
	v_mfma_f32_16x16x32_bf16 v[4:7], v[128:131], v[200:203], v[4:7]
	v_mfma_f32_16x16x32_bf16 v[0:3], v[152:155], v[200:203], v[0:3]
	v_mfma_f32_16x16x32_bf16 v[48:51], v[132:135], v[164:167], v[48:51]
	v_mfma_f32_16x16x32_bf16 v[40:43], v[156:159], v[164:167], v[40:43]
	v_mfma_f32_16x16x32_bf16 v[20:23], v[132:135], v[172:175], v[20:23]
	v_mfma_f32_16x16x32_bf16 v[16:19], v[156:159], v[172:175], v[16:19]
	v_mfma_f32_16x16x32_bf16 v[12:15], v[132:135], v[196:199], v[12:15]
	v_mfma_f32_16x16x32_bf16 v[8:11], v[156:159], v[196:199], v[8:11]
	v_mfma_f32_16x16x32_bf16 v[4:7], v[132:135], v[204:207], v[4:7]
	v_mfma_f32_16x16x32_bf16 v[0:3], v[156:159], v[204:207], v[0:3]
	s_barrier
	s_add_i32 s28, 0, 0x18000
	s_add_i32 s29, 0, 0x1c000
	ds_read_b128 v[80:83], v226 offset:32768
	ds_read_b128 v[84:87], v226 offset:33792
	ds_read_b128 v[88:91], v226 offset:34816
	ds_read_b128 v[92:95], v226 offset:35840
	ds_read_b128 v[128:131], v226 offset:49152
	ds_read_b128 v[132:135], v226 offset:50176
	ds_read_b128 v[152:155], v226 offset:51200
	ds_read_b128 v[156:159], v226 offset:52224
	s_add_u32 s26, s88, 0x40000
	s_addc_u32 s27, s89, 0
	s_mov_b32 m0, s22
	ds_read_b128 v[160:163], v228 offset:32768
	ds_read_b128 v[164:167], v228 offset:33792
	ds_read_b128 v[168:171], v228 offset:34816
	ds_read_b128 v[172:175], v228 offset:35840
	ds_read_b128 v[192:195], v228 offset:36864
	ds_read_b128 v[196:199], v228 offset:37888
	ds_read_b128 v[200:203], v228 offset:38912
	ds_read_b128 v[204:207], v228 offset:39936
	global_load_lds_dwordx4 v176, s[26:27]
	s_mov_b32 m0, s23
	s_nop 0
	global_load_lds_dwordx4 v180, s[26:27]
	s_waitcnt vmcnt(8)
	s_waitcnt lgkmcnt(0)
	s_barrier
	s_waitcnt lgkmcnt(0)
	v_mfma_f32_16x16x32_bf16 v[76:79], v[80:83], v[160:163], v[76:79]
	v_mfma_f32_16x16x32_bf16 v[64:67], v[88:91], v[160:163], v[64:67]
	v_mfma_f32_16x16x32_bf16 v[148:151], v[80:83], v[168:171], v[148:151]
	v_mfma_f32_16x16x32_bf16 v[140:143], v[88:91], v[168:171], v[140:143]
	v_mfma_f32_16x16x32_bf16 v[124:127], v[80:83], v[192:195], v[124:127]
	v_mfma_f32_16x16x32_bf16 v[120:123], v[88:91], v[192:195], v[120:123]
	v_mfma_f32_16x16x32_bf16 v[72:75], v[80:83], v[200:203], v[72:75]
	v_mfma_f32_16x16x32_bf16 v[60:63], v[88:91], v[200:203], v[60:63]
	v_mfma_f32_16x16x32_bf16 v[76:79], v[84:87], v[164:167], v[76:79]
	v_mfma_f32_16x16x32_bf16 v[64:67], v[92:95], v[164:167], v[64:67]
	v_mfma_f32_16x16x32_bf16 v[148:151], v[84:87], v[172:175], v[148:151]
	v_mfma_f32_16x16x32_bf16 v[140:143], v[92:95], v[172:175], v[140:143]
	v_mfma_f32_16x16x32_bf16 v[124:127], v[84:87], v[196:199], v[124:127]
	v_mfma_f32_16x16x32_bf16 v[120:123], v[92:95], v[196:199], v[120:123]
	v_mfma_f32_16x16x32_bf16 v[72:75], v[84:87], v[204:207], v[72:75]
	v_mfma_f32_16x16x32_bf16 v[60:63], v[92:95], v[204:207], v[60:63]
	v_mfma_f32_16x16x32_bf16 v[144:147], v[128:131], v[160:163], v[144:147]
	v_mfma_f32_16x16x32_bf16 v[136:139], v[152:155], v[160:163], v[136:139]
	v_mfma_f32_16x16x32_bf16 v[116:119], v[128:131], v[168:171], v[116:119]
	v_mfma_f32_16x16x32_bf16 v[112:115], v[152:155], v[168:171], v[112:115]
	v_mfma_f32_16x16x32_bf16 v[108:111], v[128:131], v[192:195], v[108:111]
	v_mfma_f32_16x16x32_bf16 v[104:107], v[152:155], v[192:195], v[104:107]
	v_mfma_f32_16x16x32_bf16 v[100:103], v[128:131], v[200:203], v[100:103]
	v_mfma_f32_16x16x32_bf16 v[96:99], v[152:155], v[200:203], v[96:99]
	v_mfma_f32_16x16x32_bf16 v[144:147], v[132:135], v[164:167], v[144:147]
	v_mfma_f32_16x16x32_bf16 v[136:139], v[156:159], v[164:167], v[136:139]
	v_mfma_f32_16x16x32_bf16 v[116:119], v[132:135], v[172:175], v[116:119]
	v_mfma_f32_16x16x32_bf16 v[112:115], v[156:159], v[172:175], v[112:115]
	v_mfma_f32_16x16x32_bf16 v[108:111], v[132:135], v[196:199], v[108:111]
	v_mfma_f32_16x16x32_bf16 v[104:107], v[156:159], v[196:199], v[104:107]
	v_mfma_f32_16x16x32_bf16 v[100:103], v[132:135], v[204:207], v[100:103]
	v_mfma_f32_16x16x32_bf16 v[96:99], v[156:159], v[204:207], v[96:99]
	s_barrier
	s_add_i32 m0, s28, s20
	s_add_u32 s26, s48, 0x80
	s_addc_u32 s27, s49, 0
	ds_read_b128 v[160:163], v228 offset:49152
	ds_read_b128 v[164:167], v228 offset:50176
	ds_read_b128 v[168:171], v228 offset:51200
	ds_read_b128 v[172:175], v228 offset:52224
	ds_read_b128 v[192:195], v228 offset:53248
	ds_read_b128 v[196:199], v228 offset:54272
	ds_read_b128 v[200:203], v228 offset:55296
	ds_read_b128 v[204:207], v228 offset:56320
	global_load_lds_dwordx4 v178, s[26:27]
	s_add_i32 m0, m0, 0x2000
	s_add_i32 s28, s29, s20
	global_load_lds_dwordx4 v182, s[26:27]
	s_add_u32 s26, s26, 0x40000
	s_addc_u32 s27, s27, 0
	s_mov_b32 m0, s28
	s_nop 0
	global_load_lds_dwordx4 v178, s[26:27]
	s_add_i32 m0, s28, 0x2000
	s_nop 0
	global_load_lds_dwordx4 v182, s[26:27]
	s_add_u32 s26, s88, 0x80
	s_addc_u32 s27, s89, 0
	s_mov_b32 m0, s71
	s_nop 0
	global_load_lds_dwordx4 v176, s[26:27]
	s_mov_b32 m0, s73
	s_nop 0
	global_load_lds_dwordx4 v180, s[26:27]
	s_add_u32 s26, s48, 0x40080
	s_addc_u32 s27, s49, 0
	s_waitcnt vmcnt(8)
	s_waitcnt lgkmcnt(0)
	s_barrier
	s_waitcnt lgkmcnt(0)
	v_mfma_f32_16x16x32_bf16 v[68:71], v[80:83], v[160:163], v[68:71]
	v_mfma_f32_16x16x32_bf16 v[36:39], v[88:91], v[160:163], v[36:39]
	v_mfma_f32_16x16x32_bf16 v[52:55], v[80:83], v[168:171], v[52:55]
	v_mfma_f32_16x16x32_bf16 v[44:47], v[88:91], v[168:171], v[44:47]
	v_mfma_f32_16x16x32_bf16 v[28:31], v[80:83], v[192:195], v[28:31]
	v_mfma_f32_16x16x32_bf16 v[24:27], v[88:91], v[192:195], v[24:27]
	v_mfma_f32_16x16x32_bf16 v[56:59], v[80:83], v[200:203], v[56:59]
	v_mfma_f32_16x16x32_bf16 v[32:35], v[88:91], v[200:203], v[32:35]
	v_mfma_f32_16x16x32_bf16 v[68:71], v[84:87], v[164:167], v[68:71]
	v_mfma_f32_16x16x32_bf16 v[36:39], v[92:95], v[164:167], v[36:39]
	v_mfma_f32_16x16x32_bf16 v[52:55], v[84:87], v[172:175], v[52:55]
	v_mfma_f32_16x16x32_bf16 v[44:47], v[92:95], v[172:175], v[44:47]
	v_mfma_f32_16x16x32_bf16 v[28:31], v[84:87], v[196:199], v[28:31]
	v_mfma_f32_16x16x32_bf16 v[24:27], v[92:95], v[196:199], v[24:27]
	v_mfma_f32_16x16x32_bf16 v[56:59], v[84:87], v[204:207], v[56:59]
	v_mfma_f32_16x16x32_bf16 v[32:35], v[92:95], v[204:207], v[32:35]
	v_mfma_f32_16x16x32_bf16 v[48:51], v[128:131], v[160:163], v[48:51]
	v_mfma_f32_16x16x32_bf16 v[40:43], v[152:155], v[160:163], v[40:43]
	v_mfma_f32_16x16x32_bf16 v[20:23], v[128:131], v[168:171], v[20:23]
	v_mfma_f32_16x16x32_bf16 v[16:19], v[152:155], v[168:171], v[16:19]
	v_mfma_f32_16x16x32_bf16 v[12:15], v[128:131], v[192:195], v[12:15]
	v_mfma_f32_16x16x32_bf16 v[8:11], v[152:155], v[192:195], v[8:11]
	v_mfma_f32_16x16x32_bf16 v[4:7], v[128:131], v[200:203], v[4:7]
	v_mfma_f32_16x16x32_bf16 v[0:3], v[152:155], v[200:203], v[0:3]
	v_mfma_f32_16x16x32_bf16 v[48:51], v[132:135], v[164:167], v[48:51]
	v_mfma_f32_16x16x32_bf16 v[40:43], v[156:159], v[164:167], v[40:43]
	v_mfma_f32_16x16x32_bf16 v[20:23], v[132:135], v[172:175], v[20:23]
	v_mfma_f32_16x16x32_bf16 v[16:19], v[156:159], v[172:175], v[16:19]
	v_mfma_f32_16x16x32_bf16 v[12:15], v[132:135], v[196:199], v[12:15]
	v_mfma_f32_16x16x32_bf16 v[8:11], v[156:159], v[196:199], v[8:11]
	v_mfma_f32_16x16x32_bf16 v[4:7], v[132:135], v[204:207], v[4:7]
	v_mfma_f32_16x16x32_bf16 v[0:3], v[156:159], v[204:207], v[0:3]
	s_barrier
	s_add_i32 s25, s25, 2
	s_add_u32 s46, s46, 0x100
	s_addc_u32 s47, s47, 0
	s_add_u32 s17, s17, 0x100
	s_addc_u32 s24, s24, 0
	s_cmp_gt_u32 s25, 13
	s_branch .LBB0_744
.Lp8_nopeel:
	s_cmp_eq_u32 s99, 0
	s_cbranch_scc0 .Lprio_LBB0_744
	s_setprio 1
